# E19 + HGRN2 gate phase (layer 1) rewritten the same way (all row loads in flight, f32 fast silu)
# speedup vs baseline: 1.0373x; 1.0061x over previous
; DI float bflo(u32 p) { return __uint_as_float(p << 16); }
; DI float bfhi(u32 p) { return __uint_as_float(p & 0xffff0000u); }
; DI void gate_phase(u16* hb, const u16* proj, int ld, int zoff, const float* w, int G, float scale) {
;     ...
;   for (int row = blockIdx.x * 8 + wv; row < MROWS; row += gridDim.x * 8) {
;     u32x2* hp = reinterpret_cast<u32x2*>(hb + (size_t)row * DM);
;     const u32x2* zp = reinterpret_cast<const u32x2*>(proj + (size_t)row * ld + zoff);
;     float o[8][4], ss[8];
; #pragma unroll
;     for (int i = 0; i < 8; ++i) {
;       const u32x2 pk = __builtin_nontemporal_load(hp + i * 64 + lane);
;       o[i][0] = bflo(pk.x); o[i][1] = bfhi(pk.x); o[i][2] = bflo(pk.y); o[i][3] = bfhi(pk.y);
;       ss[i] = o[i][0] * o[i][0] + o[i][1] * o[i][1] + o[i][2] * o[i][2] + o[i][3] * o[i][3];
;     }
; #pragma unroll
;     for (int i = 0; i < 8; ++i) ss[i] = wave_sum(ss[i]);
.LBB0_728:
	v_ashrrev_i32_e32 v5, 31, v4
	v_lshlrev_b64 v[0:1], 12, v[4:5]
	v_lshl_add_u64 v[20:21], v[18:19], 0, v[0:1]
	v_lshlrev_b64 v[0:1], 14, v[4:5]
	v_lshl_add_u64 v[22:23], v[6:7], 0, v[0:1]
	v_add_u32_e32 v4, s10, v4
	global_load_dwordx2 v[100:101], v[20:21], off nt
	global_load_dwordx2 v[102:103], v[20:21], off offset:512 nt
	global_load_dwordx2 v[104:105], v[20:21], off offset:1024 nt
	global_load_dwordx2 v[106:107], v[20:21], off offset:1536 nt
	global_load_dwordx2 v[108:109], v[20:21], off offset:2048 nt
	global_load_dwordx2 v[110:111], v[20:21], off offset:2560 nt
	global_load_dwordx2 v[112:113], v[20:21], off offset:3072 nt
	global_load_dwordx2 v[114:115], v[20:21], off offset:3584 nt
	global_load_dwordx4 v[212:215], v[8:9], off
	global_load_dwordx4 v[216:219], v[8:9], off offset:1024
	global_load_dwordx4 v[220:223], v[8:9], off offset:2048
	global_load_dwordx4 v[224:227], v[8:9], off offset:3072
	global_load_dwordx4 v[228:231], v[10:11], off
	global_load_dwordx4 v[232:235], v[12:13], off
	global_load_dwordx4 v[236:239], v[14:15], off
	global_load_dwordx4 v[240:243], v[16:17], off
	global_load_dwordx2 v[116:117], v[22:23], off nt
	global_load_dwordx2 v[118:119], v[22:23], off offset:512 nt
	global_load_dwordx2 v[120:121], v[22:23], off offset:1024 nt
	global_load_dwordx2 v[122:123], v[22:23], off offset:1536 nt
	global_load_dwordx2 v[124:125], v[22:23], off offset:2048 nt
	global_load_dwordx2 v[126:127], v[22:23], off offset:2560 nt
	global_load_dwordx2 v[128:129], v[22:23], off offset:3072 nt
	global_load_dwordx2 v[130:131], v[22:23], off offset:3584 nt
	s_waitcnt vmcnt(23)
	v_lshlrev_b32_e32 v140, 16, v100
	v_and_b32_e32 v141, 0xffff0000, v100
	v_lshlrev_b32_e32 v142, 16, v101
	v_and_b32_e32 v143, 0xffff0000, v101
	v_mul_f32_e32 v172, v140, v140
	v_fmac_f32_e32 v172, v141, v141
	v_fmac_f32_e32 v172, v142, v142
	v_fmac_f32_e32 v172, v143, v143
	s_waitcnt vmcnt(22)
	v_lshlrev_b32_e32 v144, 16, v102
	v_and_b32_e32 v145, 0xffff0000, v102
	v_lshlrev_b32_e32 v146, 16, v103
	v_and_b32_e32 v147, 0xffff0000, v103
	v_mul_f32_e32 v173, v144, v144
	v_fmac_f32_e32 v173, v145, v145
	v_fmac_f32_e32 v173, v146, v146
	v_fmac_f32_e32 v173, v147, v147
	s_waitcnt vmcnt(21)
	v_lshlrev_b32_e32 v148, 16, v104
	v_and_b32_e32 v149, 0xffff0000, v104
	v_lshlrev_b32_e32 v150, 16, v105
	v_and_b32_e32 v151, 0xffff0000, v105
	v_mul_f32_e32 v174, v148, v148
	v_fmac_f32_e32 v174, v149, v149
	v_fmac_f32_e32 v174, v150, v150
	v_fmac_f32_e32 v174, v151, v151
	s_waitcnt vmcnt(20)
	v_lshlrev_b32_e32 v152, 16, v106
	v_and_b32_e32 v153, 0xffff0000, v106
	v_lshlrev_b32_e32 v154, 16, v107
	v_and_b32_e32 v155, 0xffff0000, v107
	v_mul_f32_e32 v175, v152, v152
	v_fmac_f32_e32 v175, v153, v153
	v_fmac_f32_e32 v175, v154, v154
	v_fmac_f32_e32 v175, v155, v155
	s_waitcnt vmcnt(19)
	v_lshlrev_b32_e32 v156, 16, v108
	v_and_b32_e32 v157, 0xffff0000, v108
	v_lshlrev_b32_e32 v158, 16, v109
	v_and_b32_e32 v159, 0xffff0000, v109
	v_mul_f32_e32 v176, v156, v156
	v_fmac_f32_e32 v176, v157, v157
	v_fmac_f32_e32 v176, v158, v158
	v_fmac_f32_e32 v176, v159, v159
	s_waitcnt vmcnt(18)
	v_lshlrev_b32_e32 v160, 16, v110
	v_and_b32_e32 v161, 0xffff0000, v110
	v_lshlrev_b32_e32 v162, 16, v111
	v_and_b32_e32 v163, 0xffff0000, v111
	v_mul_f32_e32 v177, v160, v160
	v_fmac_f32_e32 v177, v161, v161
	v_fmac_f32_e32 v177, v162, v162
	v_fmac_f32_e32 v177, v163, v163
	s_waitcnt vmcnt(17)
	v_lshlrev_b32_e32 v164, 16, v112
	v_and_b32_e32 v165, 0xffff0000, v112
	v_lshlrev_b32_e32 v166, 16, v113
	v_and_b32_e32 v167, 0xffff0000, v113
	v_mul_f32_e32 v178, v164, v164
	v_fmac_f32_e32 v178, v165, v165
	v_fmac_f32_e32 v178, v166, v166
	v_fmac_f32_e32 v178, v167, v167
	s_waitcnt vmcnt(16)
	v_lshlrev_b32_e32 v168, 16, v114
	v_and_b32_e32 v169, 0xffff0000, v114
	v_lshlrev_b32_e32 v170, 16, v115
	v_and_b32_e32 v171, 0xffff0000, v115
	v_mul_f32_e32 v179, v168, v168
	v_fmac_f32_e32 v179, v169, v169
	v_fmac_f32_e32 v179, v170, v170
	v_fmac_f32_e32 v179, v171, v171
	ds_bpermute_b32 v180, v62, v172
	ds_bpermute_b32 v181, v62, v173
	ds_bpermute_b32 v182, v62, v174
	ds_bpermute_b32 v183, v62, v175
	ds_bpermute_b32 v184, v62, v176
	ds_bpermute_b32 v185, v62, v177
	ds_bpermute_b32 v186, v62, v178
	ds_bpermute_b32 v187, v62, v179
	s_waitcnt lgkmcnt(0)
	v_add_f32_e32 v172, v172, v180
	v_add_f32_e32 v173, v173, v181
	v_add_f32_e32 v174, v174, v182
	v_add_f32_e32 v175, v175, v183
	v_add_f32_e32 v176, v176, v184
	v_add_f32_e32 v177, v177, v185
	v_add_f32_e32 v178, v178, v186
	v_add_f32_e32 v179, v179, v187
	ds_bpermute_b32 v180, v63, v172
	ds_bpermute_b32 v181, v63, v173
	ds_bpermute_b32 v182, v63, v174
	ds_bpermute_b32 v183, v63, v175
	ds_bpermute_b32 v184, v63, v176
	ds_bpermute_b32 v185, v63, v177
	ds_bpermute_b32 v186, v63, v178
	ds_bpermute_b32 v187, v63, v179
	s_waitcnt lgkmcnt(0)
	v_add_f32_e32 v172, v172, v180
	v_add_f32_e32 v173, v173, v181
	v_add_f32_e32 v174, v174, v182
	v_add_f32_e32 v175, v175, v183
	v_add_f32_e32 v176, v176, v184
	v_add_f32_e32 v177, v177, v185
	v_add_f32_e32 v178, v178, v186
	v_add_f32_e32 v179, v179, v187
	ds_bpermute_b32 v180, v64, v172
	ds_bpermute_b32 v181, v64, v173
	ds_bpermute_b32 v182, v64, v174
	ds_bpermute_b32 v183, v64, v175
	ds_bpermute_b32 v184, v64, v176
	ds_bpermute_b32 v185, v64, v177
	ds_bpermute_b32 v186, v64, v178
	ds_bpermute_b32 v187, v64, v179
	s_waitcnt lgkmcnt(0)
	v_add_f32_e32 v172, v172, v180
	v_add_f32_e32 v173, v173, v181
	v_add_f32_e32 v174, v174, v182
	v_add_f32_e32 v175, v175, v183
	v_add_f32_e32 v176, v176, v184
	v_add_f32_e32 v177, v177, v185
	v_add_f32_e32 v178, v178, v186
	v_add_f32_e32 v179, v179, v187
	ds_bpermute_b32 v180, v65, v172
	ds_bpermute_b32 v181, v65, v173
	ds_bpermute_b32 v182, v65, v174
	ds_bpermute_b32 v183, v65, v175
	ds_bpermute_b32 v184, v65, v176
	ds_bpermute_b32 v185, v65, v177
	ds_bpermute_b32 v186, v65, v178
	ds_bpermute_b32 v187, v65, v179
	s_waitcnt lgkmcnt(0)
; DI u32 pack2(float a, float b) { f32v2 v = {a, b}; return __builtin_bit_cast(u32, __builtin_convertvector(v, bf16v2)); }
; DI float bflo(u32 p) { return __uint_as_float(p << 16); }
; DI float bfhi(u32 p) { return __uint_as_float(p & 0xffff0000u); }
; DI void gate_phase(u16* hb, const u16* proj, int ld, int zoff, const float* w, int G, float scale) {
;     ...
;     for (int i = 0; i < 8; ++i) ss[i] = wave_sum(ss[i]);
;     if (G == 512) {
; #pragma unroll
;       for (int i = 0; i < 8; i += 2) { const float t = ss[i] + ss[i + 1]; ss[i] = t; ss[i + 1] = t; }
;     } else if (G == 2048) {
;       float t = 0.f;
; #pragma unroll
;       for (int i = 0; i < 8; ++i) t += ss[i];
; #pragma unroll
;       for (int i = 0; i < 8; ++i) ss[i] = t;
;     }
;     const float invG = 1.f / (float)G;
; #pragma unroll
;     for (int i = 0; i < 8; ++i) {
;       const float r = rsqrtf(ss[i] * invG + 1e-6f) * scale;
;       const int col = i * 256 + lane * 4;
;       const float4 ww = *reinterpret_cast<const float4*>(w + (col & (G - 1)));
;       const u32x2 zk = __builtin_nontemporal_load(zp + i * 64 + lane);
;       const float z0 = bflo(zk.x), z1 = bfhi(zk.x), z2 = bflo(zk.y), z3 = bfhi(zk.y);
;       const float g0 = o[i][0] * r * ww.x * (z0 / (1.f + expf(-z0)));
;       const float g1 = o[i][1] * r * ww.y * (z1 / (1.f + expf(-z1)));
;       const float g2 = o[i][2] * r * ww.z * (z2 / (1.f + expf(-z2)));
;       const float g3 = o[i][3] * r * ww.w * (z3 / (1.f + expf(-z3)));
;       u32x2 ov = {pack2(g0, g1), pack2(g2, g3)};
;       hp[i * 64 + lane] = ov;
	v_add_f32_e32 v172, v172, v180
	v_add_f32_e32 v173, v173, v181
	v_add_f32_e32 v174, v174, v182
	v_add_f32_e32 v175, v175, v183
	v_add_f32_e32 v176, v176, v184
	v_add_f32_e32 v177, v177, v185
	v_add_f32_e32 v178, v178, v186
	v_add_f32_e32 v179, v179, v187
	ds_bpermute_b32 v180, v66, v172
	ds_bpermute_b32 v181, v66, v173
	ds_bpermute_b32 v182, v66, v174
	ds_bpermute_b32 v183, v66, v175
	ds_bpermute_b32 v184, v66, v176
	ds_bpermute_b32 v185, v66, v177
	ds_bpermute_b32 v186, v66, v178
	ds_bpermute_b32 v187, v66, v179
	s_waitcnt lgkmcnt(0)
	v_add_f32_e32 v172, v172, v180
	v_add_f32_e32 v173, v173, v181
	v_add_f32_e32 v174, v174, v182
	v_add_f32_e32 v175, v175, v183
	v_add_f32_e32 v176, v176, v184
	v_add_f32_e32 v177, v177, v185
	v_add_f32_e32 v178, v178, v186
	v_add_f32_e32 v179, v179, v187
	ds_bpermute_b32 v180, v67, v172
	ds_bpermute_b32 v181, v67, v173
	ds_bpermute_b32 v182, v67, v174
	ds_bpermute_b32 v183, v67, v175
	ds_bpermute_b32 v184, v67, v176
	ds_bpermute_b32 v185, v67, v177
	ds_bpermute_b32 v186, v67, v178
	ds_bpermute_b32 v187, v67, v179
	s_waitcnt lgkmcnt(0)
	v_add_f32_e32 v172, v172, v180
	v_add_f32_e32 v173, v173, v181
	v_add_f32_e32 v174, v174, v182
	v_add_f32_e32 v175, v175, v183
	v_add_f32_e32 v176, v176, v184
	v_add_f32_e32 v177, v177, v185
	v_add_f32_e32 v178, v178, v186
	v_add_f32_e32 v179, v179, v187
	v_add_f32_e32 v180, v172, v173
	v_add_f32_e32 v180, v180, v174
	v_add_f32_e32 v180, v180, v175
	v_add_f32_e32 v180, v180, v176
	v_add_f32_e32 v180, v180, v177
	v_add_f32_e32 v180, v180, v178
	v_add_f32_e32 v180, v180, v179
	v_fmamk_f32 v180, v180, 0x3a000000, v69
	v_rsq_f32_e32 v180, v180
	s_waitcnt vmcnt(0)
	v_lshlrev_b32_e32 v188, 16, v116
	v_and_b32_e32 v189, 0xffff0000, v116
	v_lshlrev_b32_e32 v190, 16, v117
	v_and_b32_e32 v191, 0xffff0000, v117
	v_mul_f32_e32 v192, 0xbfb8aa3b, v188
	v_mul_f32_e32 v193, 0xbfb8aa3b, v189
	v_mul_f32_e32 v194, 0xbfb8aa3b, v190
	v_mul_f32_e32 v195, 0xbfb8aa3b, v191
	v_exp_f32_e32 v192, v192
	v_exp_f32_e32 v193, v193
	v_exp_f32_e32 v194, v194
	v_exp_f32_e32 v195, v195
	v_mul_f32_e32 v140, v140, v180
	v_mul_f32_e32 v141, v141, v180
	v_mul_f32_e32 v142, v142, v180
	v_mul_f32_e32 v143, v143, v180
	v_add_f32_e32 v192, 1.0, v192
	v_add_f32_e32 v193, 1.0, v193
	v_add_f32_e32 v194, 1.0, v194
	v_add_f32_e32 v195, 1.0, v195
	v_rcp_f32_e32 v192, v192
	v_rcp_f32_e32 v193, v193
	v_rcp_f32_e32 v194, v194
	v_rcp_f32_e32 v195, v195
	v_mul_f32_e32 v140, v140, v212
	v_mul_f32_e32 v141, v141, v213
	v_mul_f32_e32 v142, v142, v214
	v_mul_f32_e32 v143, v143, v215
	v_mul_f32_e32 v192, v188, v192
	v_mul_f32_e32 v193, v189, v193
	v_mul_f32_e32 v194, v190, v194
	v_mul_f32_e32 v195, v191, v195
	v_mul_f32_e32 v140, v140, v192
	v_mul_f32_e32 v141, v141, v193
	v_mul_f32_e32 v142, v142, v194
	v_mul_f32_e32 v143, v143, v195
	v_cvt_pk_bf16_f32 v196, v140, v141
	v_cvt_pk_bf16_f32 v197, v142, v143
	global_store_dwordx2 v[20:21], v[196:197], off
	v_lshlrev_b32_e32 v188, 16, v118
	v_and_b32_e32 v189, 0xffff0000, v118
	v_lshlrev_b32_e32 v190, 16, v119
	v_and_b32_e32 v191, 0xffff0000, v119
	v_mul_f32_e32 v192, 0xbfb8aa3b, v188
	v_mul_f32_e32 v193, 0xbfb8aa3b, v189
	v_mul_f32_e32 v194, 0xbfb8aa3b, v190
	v_mul_f32_e32 v195, 0xbfb8aa3b, v191
	v_exp_f32_e32 v192, v192
	v_exp_f32_e32 v193, v193
	v_exp_f32_e32 v194, v194
	v_exp_f32_e32 v195, v195
	v_mul_f32_e32 v144, v144, v180
	v_mul_f32_e32 v145, v145, v180
	v_mul_f32_e32 v146, v146, v180
	v_mul_f32_e32 v147, v147, v180
	v_add_f32_e32 v192, 1.0, v192
	v_add_f32_e32 v193, 1.0, v193
	v_add_f32_e32 v194, 1.0, v194
	v_add_f32_e32 v195, 1.0, v195
	v_rcp_f32_e32 v192, v192
	v_rcp_f32_e32 v193, v193
	v_rcp_f32_e32 v194, v194
	v_rcp_f32_e32 v195, v195
	v_mul_f32_e32 v144, v144, v216
	v_mul_f32_e32 v145, v145, v217
	v_mul_f32_e32 v146, v146, v218
	v_mul_f32_e32 v147, v147, v219
	v_mul_f32_e32 v192, v188, v192
	v_mul_f32_e32 v193, v189, v193
	v_mul_f32_e32 v194, v190, v194
	v_mul_f32_e32 v195, v191, v195
	v_mul_f32_e32 v144, v144, v192
	v_mul_f32_e32 v145, v145, v193
	v_mul_f32_e32 v146, v146, v194
	v_mul_f32_e32 v147, v147, v195
	v_cvt_pk_bf16_f32 v198, v144, v145
	v_cvt_pk_bf16_f32 v199, v146, v147
	global_store_dwordx2 v[20:21], v[198:199], off offset:512
	v_lshlrev_b32_e32 v188, 16, v120
	v_and_b32_e32 v189, 0xffff0000, v120
	v_lshlrev_b32_e32 v190, 16, v121
	v_and_b32_e32 v191, 0xffff0000, v121
	v_mul_f32_e32 v192, 0xbfb8aa3b, v188
	v_mul_f32_e32 v193, 0xbfb8aa3b, v189
	v_mul_f32_e32 v194, 0xbfb8aa3b, v190
	v_mul_f32_e32 v195, 0xbfb8aa3b, v191
	v_exp_f32_e32 v192, v192
	v_exp_f32_e32 v193, v193
	v_exp_f32_e32 v194, v194
	v_exp_f32_e32 v195, v195
	v_mul_f32_e32 v148, v148, v180
	v_mul_f32_e32 v149, v149, v180
	v_mul_f32_e32 v150, v150, v180
	v_mul_f32_e32 v151, v151, v180
	v_add_f32_e32 v192, 1.0, v192
	v_add_f32_e32 v193, 1.0, v193
	v_add_f32_e32 v194, 1.0, v194
	v_add_f32_e32 v195, 1.0, v195
	v_rcp_f32_e32 v192, v192
	v_rcp_f32_e32 v193, v193
	v_rcp_f32_e32 v194, v194
	v_rcp_f32_e32 v195, v195
	v_mul_f32_e32 v148, v148, v220
	v_mul_f32_e32 v149, v149, v221
	v_mul_f32_e32 v150, v150, v222
	v_mul_f32_e32 v151, v151, v223
	v_mul_f32_e32 v192, v188, v192
	v_mul_f32_e32 v193, v189, v193
	v_mul_f32_e32 v194, v190, v194
	v_mul_f32_e32 v195, v191, v195
	v_mul_f32_e32 v148, v148, v192
	v_mul_f32_e32 v149, v149, v193
	v_mul_f32_e32 v150, v150, v194
	v_mul_f32_e32 v151, v151, v195
	v_cvt_pk_bf16_f32 v196, v148, v149
	v_cvt_pk_bf16_f32 v197, v150, v151
	global_store_dwordx2 v[20:21], v[196:197], off offset:1024
	v_lshlrev_b32_e32 v188, 16, v122
	v_and_b32_e32 v189, 0xffff0000, v122
	v_lshlrev_b32_e32 v190, 16, v123
	v_and_b32_e32 v191, 0xffff0000, v123
	v_mul_f32_e32 v192, 0xbfb8aa3b, v188
; DI u32 pack2(float a, float b) { f32v2 v = {a, b}; return __builtin_bit_cast(u32, __builtin_convertvector(v, bf16v2)); }
; DI float bflo(u32 p) { return __uint_as_float(p << 16); }
; DI float bfhi(u32 p) { return __uint_as_float(p & 0xffff0000u); }
; DI void gate_phase(u16* hb, const u16* proj, int ld, int zoff, const float* w, int G, float scale) {
;     ...
;     for (int i = 0; i < 8; ++i) {
;       const float r = rsqrtf(ss[i] * invG + 1e-6f) * scale;
;       const int col = i * 256 + lane * 4;
;       const float4 ww = *reinterpret_cast<const float4*>(w + (col & (G - 1)));
;       const u32x2 zk = __builtin_nontemporal_load(zp + i * 64 + lane);
;       const float z0 = bflo(zk.x), z1 = bfhi(zk.x), z2 = bflo(zk.y), z3 = bfhi(zk.y);
;       const float g0 = o[i][0] * r * ww.x * (z0 / (1.f + expf(-z0)));
;       const float g1 = o[i][1] * r * ww.y * (z1 / (1.f + expf(-z1)));
;       const float g2 = o[i][2] * r * ww.z * (z2 / (1.f + expf(-z2)));
;       const float g3 = o[i][3] * r * ww.w * (z3 / (1.f + expf(-z3)));
;       u32x2 ov = {pack2(g0, g1), pack2(g2, g3)};
;       hp[i * 64 + lane] = ov;
;     }
;   }
	v_mul_f32_e32 v193, 0xbfb8aa3b, v189
	v_mul_f32_e32 v194, 0xbfb8aa3b, v190
	v_mul_f32_e32 v195, 0xbfb8aa3b, v191
	v_exp_f32_e32 v192, v192
	v_exp_f32_e32 v193, v193
	v_exp_f32_e32 v194, v194
	v_exp_f32_e32 v195, v195
	v_mul_f32_e32 v152, v152, v180
	v_mul_f32_e32 v153, v153, v180
	v_mul_f32_e32 v154, v154, v180
	v_mul_f32_e32 v155, v155, v180
	v_add_f32_e32 v192, 1.0, v192
	v_add_f32_e32 v193, 1.0, v193
	v_add_f32_e32 v194, 1.0, v194
	v_add_f32_e32 v195, 1.0, v195
	v_rcp_f32_e32 v192, v192
	v_rcp_f32_e32 v193, v193
	v_rcp_f32_e32 v194, v194
	v_rcp_f32_e32 v195, v195
	v_mul_f32_e32 v152, v152, v224
	v_mul_f32_e32 v153, v153, v225
	v_mul_f32_e32 v154, v154, v226
	v_mul_f32_e32 v155, v155, v227
	v_mul_f32_e32 v192, v188, v192
	v_mul_f32_e32 v193, v189, v193
	v_mul_f32_e32 v194, v190, v194
	v_mul_f32_e32 v195, v191, v195
	v_mul_f32_e32 v152, v152, v192
	v_mul_f32_e32 v153, v153, v193
	v_mul_f32_e32 v154, v154, v194
	v_mul_f32_e32 v155, v155, v195
	v_cvt_pk_bf16_f32 v198, v152, v153
	v_cvt_pk_bf16_f32 v199, v154, v155
	global_store_dwordx2 v[20:21], v[198:199], off offset:1536
	v_lshlrev_b32_e32 v188, 16, v124
	v_and_b32_e32 v189, 0xffff0000, v124
	v_lshlrev_b32_e32 v190, 16, v125
	v_and_b32_e32 v191, 0xffff0000, v125
	v_mul_f32_e32 v192, 0xbfb8aa3b, v188
	v_mul_f32_e32 v193, 0xbfb8aa3b, v189
	v_mul_f32_e32 v194, 0xbfb8aa3b, v190
	v_mul_f32_e32 v195, 0xbfb8aa3b, v191
	v_exp_f32_e32 v192, v192
	v_exp_f32_e32 v193, v193
	v_exp_f32_e32 v194, v194
	v_exp_f32_e32 v195, v195
	v_mul_f32_e32 v156, v156, v180
	v_mul_f32_e32 v157, v157, v180
	v_mul_f32_e32 v158, v158, v180
	v_mul_f32_e32 v159, v159, v180
	v_add_f32_e32 v192, 1.0, v192
	v_add_f32_e32 v193, 1.0, v193
	v_add_f32_e32 v194, 1.0, v194
	v_add_f32_e32 v195, 1.0, v195
	v_rcp_f32_e32 v192, v192
	v_rcp_f32_e32 v193, v193
	v_rcp_f32_e32 v194, v194
	v_rcp_f32_e32 v195, v195
	v_mul_f32_e32 v156, v156, v228
	v_mul_f32_e32 v157, v157, v229
	v_mul_f32_e32 v158, v158, v230
	v_mul_f32_e32 v159, v159, v231
	v_mul_f32_e32 v192, v188, v192
	v_mul_f32_e32 v193, v189, v193
	v_mul_f32_e32 v194, v190, v194
	v_mul_f32_e32 v195, v191, v195
	v_mul_f32_e32 v156, v156, v192
	v_mul_f32_e32 v157, v157, v193
	v_mul_f32_e32 v158, v158, v194
	v_mul_f32_e32 v159, v159, v195
	v_cvt_pk_bf16_f32 v196, v156, v157
	v_cvt_pk_bf16_f32 v197, v158, v159
	global_store_dwordx2 v[20:21], v[196:197], off offset:2048
	v_lshlrev_b32_e32 v188, 16, v126
	v_and_b32_e32 v189, 0xffff0000, v126
	v_lshlrev_b32_e32 v190, 16, v127
	v_and_b32_e32 v191, 0xffff0000, v127
	v_mul_f32_e32 v192, 0xbfb8aa3b, v188
	v_mul_f32_e32 v193, 0xbfb8aa3b, v189
	v_mul_f32_e32 v194, 0xbfb8aa3b, v190
	v_mul_f32_e32 v195, 0xbfb8aa3b, v191
	v_exp_f32_e32 v192, v192
	v_exp_f32_e32 v193, v193
	v_exp_f32_e32 v194, v194
	v_exp_f32_e32 v195, v195
	v_mul_f32_e32 v160, v160, v180
	v_mul_f32_e32 v161, v161, v180
	v_mul_f32_e32 v162, v162, v180
	v_mul_f32_e32 v163, v163, v180
	v_add_f32_e32 v192, 1.0, v192
	v_add_f32_e32 v193, 1.0, v193
	v_add_f32_e32 v194, 1.0, v194
	v_add_f32_e32 v195, 1.0, v195
	v_rcp_f32_e32 v192, v192
	v_rcp_f32_e32 v193, v193
	v_rcp_f32_e32 v194, v194
	v_rcp_f32_e32 v195, v195
	v_mul_f32_e32 v160, v160, v232
	v_mul_f32_e32 v161, v161, v233
	v_mul_f32_e32 v162, v162, v234
	v_mul_f32_e32 v163, v163, v235
	v_mul_f32_e32 v192, v188, v192
	v_mul_f32_e32 v193, v189, v193
	v_mul_f32_e32 v194, v190, v194
	v_mul_f32_e32 v195, v191, v195
	v_mul_f32_e32 v160, v160, v192
	v_mul_f32_e32 v161, v161, v193
	v_mul_f32_e32 v162, v162, v194
	v_mul_f32_e32 v163, v163, v195
	v_cvt_pk_bf16_f32 v198, v160, v161
	v_cvt_pk_bf16_f32 v199, v162, v163
	global_store_dwordx2 v[20:21], v[198:199], off offset:2560
	v_lshlrev_b32_e32 v188, 16, v128
	v_and_b32_e32 v189, 0xffff0000, v128
	v_lshlrev_b32_e32 v190, 16, v129
	v_and_b32_e32 v191, 0xffff0000, v129
	v_mul_f32_e32 v192, 0xbfb8aa3b, v188
	v_mul_f32_e32 v193, 0xbfb8aa3b, v189
	v_mul_f32_e32 v194, 0xbfb8aa3b, v190
	v_mul_f32_e32 v195, 0xbfb8aa3b, v191
	v_exp_f32_e32 v192, v192
	v_exp_f32_e32 v193, v193
	v_exp_f32_e32 v194, v194
	v_exp_f32_e32 v195, v195
	v_mul_f32_e32 v164, v164, v180
	v_mul_f32_e32 v165, v165, v180
	v_mul_f32_e32 v166, v166, v180
	v_mul_f32_e32 v167, v167, v180
	v_add_f32_e32 v192, 1.0, v192
	v_add_f32_e32 v193, 1.0, v193
	v_add_f32_e32 v194, 1.0, v194
	v_add_f32_e32 v195, 1.0, v195
	v_rcp_f32_e32 v192, v192
	v_rcp_f32_e32 v193, v193
	v_rcp_f32_e32 v194, v194
	v_rcp_f32_e32 v195, v195
	v_mul_f32_e32 v164, v164, v236
	v_mul_f32_e32 v165, v165, v237
	v_mul_f32_e32 v166, v166, v238
	v_mul_f32_e32 v167, v167, v239
	v_mul_f32_e32 v192, v188, v192
	v_mul_f32_e32 v193, v189, v193
	v_mul_f32_e32 v194, v190, v194
	v_mul_f32_e32 v195, v191, v195
	v_mul_f32_e32 v164, v164, v192
	v_mul_f32_e32 v165, v165, v193
	v_mul_f32_e32 v166, v166, v194
	v_mul_f32_e32 v167, v167, v195
	v_cvt_pk_bf16_f32 v196, v164, v165
	v_cvt_pk_bf16_f32 v197, v166, v167
	global_store_dwordx2 v[20:21], v[196:197], off offset:3072
	v_lshlrev_b32_e32 v188, 16, v130
	v_and_b32_e32 v189, 0xffff0000, v130
	v_lshlrev_b32_e32 v190, 16, v131
	v_and_b32_e32 v191, 0xffff0000, v131
	v_mul_f32_e32 v192, 0xbfb8aa3b, v188
	v_mul_f32_e32 v193, 0xbfb8aa3b, v189
	v_mul_f32_e32 v194, 0xbfb8aa3b, v190
	v_mul_f32_e32 v195, 0xbfb8aa3b, v191
	v_exp_f32_e32 v192, v192
	v_exp_f32_e32 v193, v193
	v_exp_f32_e32 v194, v194
	v_exp_f32_e32 v195, v195
	v_mul_f32_e32 v168, v168, v180
	v_mul_f32_e32 v169, v169, v180
	v_mul_f32_e32 v170, v170, v180
	v_mul_f32_e32 v171, v171, v180
	v_add_f32_e32 v192, 1.0, v192
	v_add_f32_e32 v193, 1.0, v193
	v_add_f32_e32 v194, 1.0, v194
	v_add_f32_e32 v195, 1.0, v195
	v_rcp_f32_e32 v192, v192
	v_rcp_f32_e32 v193, v193
	v_rcp_f32_e32 v194, v194
	v_rcp_f32_e32 v195, v195
	v_mul_f32_e32 v168, v168, v240
	v_mul_f32_e32 v169, v169, v241
	v_mul_f32_e32 v170, v170, v242
	v_mul_f32_e32 v171, v171, v243
	v_mul_f32_e32 v192, v188, v192
	v_mul_f32_e32 v193, v189, v193
	v_mul_f32_e32 v194, v190, v194
	v_mul_f32_e32 v195, v191, v195
	v_mul_f32_e32 v168, v168, v192
	v_mul_f32_e32 v169, v169, v193
	v_mul_f32_e32 v170, v170, v194
	v_mul_f32_e32 v171, v171, v195
	v_cvt_pk_bf16_f32 v198, v168, v169
	v_cvt_pk_bf16_f32 v199, v170, v171
	global_store_dwordx2 v[20:21], v[198:199], off offset:3584
	v_cmp_lt_i32_e32 vcc, s15, v4
	s_nop 1
	s_or_b64 s[8:9], vcc, s[8:9]
	s_andn2_b64 exec, exec, s[8:9]
	s_cbranch_execnz .LBB0_728
